# grid barrier: non-leader workgroups poll the top-level generation word directly instead of the per-XCD generation (one hop less)
# speedup vs baseline: 1.0003x; 1.0003x over previous
; __device__ __forceinline__ unsigned xb_ld(unsigned* p)              { return __hip_atomic_load(p, __ATOMIC_RELAXED, __HIP_MEMORY_SCOPE_AGENT); }
; __device__ __forceinline__ unsigned xb_add(unsigned* p, unsigned v) { return __hip_atomic_fetch_add(p, v, __ATOMIC_RELAXED, __HIP_MEMORY_SCOPE_AGENT); }
; #define XB_SPIN(cond, bar) do { unsigned _sp = 0; while (cond) { __builtin_amdgcn_s_sleep(1); \
;     if ((++_sp & 255u) == 0u) { if (xb_ld(&(bar)[XB_TMO])) break; if (_sp > XB_SPIN_CAP) { atomicAdd(&(bar)[XB_TMO], 1u); break; } } } } while (0)
; __device__ __forceinline__ void xcd_barrier(const XcdBarrier& b) {
;     ...
;         const unsigned old = xb_add(&bar[XB_XSUB(b.x)], 1u);
;         const unsigned gen = old / nloc;
;         if (old + 1u == (gen + 1u) * nloc) {
;             __builtin_amdgcn_fence(__ATOMIC_RELEASE, "agent");
;             asm volatile("s_waitcnt vmcnt(0)" ::: "memory");
;             const unsigned og = xb_add(&bar[XB_TOP], 1u);
;             const unsigned tg = og / nx;
;             if (og + 1u == (tg + 1u) * nx) xb_add(&bar[XB_TOPGEN], 1u);
;             else XB_SPIN(xb_ld(&bar[XB_TOPGEN]) == tg, bar);
;             __builtin_amdgcn_fence(__ATOMIC_ACQUIRE, "agent");
;             xb_add(&bar[XB_XGEN(b.x)], 1u);
;             asm volatile("s_waitcnt vmcnt(0)" ::: "memory");
;         } else {
;             XB_SPIN(xb_ld(&bar[XB_XGEN(b.x)]) == gen, bar);
.LBB0_433:
	s_or_b64 exec, exec, s[6:7]
	v_cvt_f32_u32_e32 v4, v2
	s_waitcnt vmcnt(0)
	v_readfirstlane_b32 s6, v3
	v_sub_u32_e32 v3, 0, v2
	v_rcp_iflag_f32_e32 v4, v4
	v_add_u32_e32 v5, s6, v1
	v_mul_f32_e32 v4, 0x4f7ffffe, v4
	v_cvt_u32_f32_e32 v4, v4
	v_mul_lo_u32 v1, v3, v4
	v_mul_hi_u32 v1, v4, v1
	v_add_u32_e32 v1, v4, v1
	v_mul_hi_u32 v1, v5, v1
	v_mul_lo_u32 v3, v1, v2
	v_sub_u32_e32 v3, v5, v3
	v_add_u32_e32 v4, 1, v1
	v_cmp_ge_u32_e32 vcc, v3, v2
	s_nop 1
	v_cndmask_b32_e32 v1, v1, v4, vcc
	v_sub_u32_e32 v4, v3, v2
	v_cndmask_b32_e32 v3, v3, v4, vcc
	v_add_u32_e32 v4, 1, v1
	v_cmp_ge_u32_e32 vcc, v3, v2
	v_add_u32_e32 v3, 1, v5
	s_nop 0
	v_cndmask_b32_e32 v1, v1, v4, vcc
	v_mul_lo_u32 v4, v2, v1
	v_add_u32_e32 v2, v4, v2
	v_cmp_ne_u32_e32 vcc, v3, v2
	s_and_saveexec_b64 s[6:7], vcc
	s_xor_b64 s[6:7], exec, s[6:7]
	s_cbranch_execz .LBB0_447
	s_waitcnt lgkmcnt(0)
	v_mov_b32_e32 v0, 0
	v_readlane_b32 s98, v242, 30
	v_readlane_b32 s99, v242, 31
	s_nop 4
	s_add_u32 s98, s98, 0x3300
	s_addc_u32 s99, s99, 0
	global_load_dword v2, v0, s[98:99] sc1
	s_waitcnt vmcnt(0)
	v_cmp_eq_u32_e32 vcc, v2, v1
	s_and_saveexec_b64 s[8:9], vcc
	s_cbranch_execz .LBB0_446
	s_mov_b32 s16, 1
	s_mov_b64 s[10:11], 0
	s_branch .LBB0_437

; __device__ __forceinline__ unsigned xb_ld(unsigned* p)              { return __hip_atomic_load(p, __ATOMIC_RELAXED, __HIP_MEMORY_SCOPE_AGENT); }
; __device__ __forceinline__ unsigned xb_add(unsigned* p, unsigned v) { return __hip_atomic_fetch_add(p, v, __ATOMIC_RELAXED, __HIP_MEMORY_SCOPE_AGENT); }
; #define XB_SPIN(cond, bar) do { unsigned _sp = 0; while (cond) { __builtin_amdgcn_s_sleep(1); \
;     if ((++_sp & 255u) == 0u) { if (xb_ld(&(bar)[XB_TMO])) break; if (_sp > XB_SPIN_CAP) { atomicAdd(&(bar)[XB_TMO], 1u); break; } } } } while (0)
; __device__ __forceinline__ void xcd_barrier(const XcdBarrier& b) {
;     ...
;             else XB_SPIN(xb_ld(&bar[XB_TOPGEN]) == tg, bar);
;             __builtin_amdgcn_fence(__ATOMIC_ACQUIRE, "agent");
;             xb_add(&bar[XB_XGEN(b.x)], 1u);
;             asm volatile("s_waitcnt vmcnt(0)" ::: "memory");
;         } else {
;             XB_SPIN(xb_ld(&bar[XB_XGEN(b.x)]) == gen, bar);
.LBB0_439:
	global_load_dword v2, v0, s[98:99] sc1
	s_add_i32 s16, s16, 1
	s_mov_b64 s[50:51], -1
	s_waitcnt vmcnt(0)
	v_cmp_ne_u32_e32 vcc, v2, v1
	s_orn2_b64 s[46:47], vcc, exec
	s_branch .LBB0_436

; __device__ __forceinline__ unsigned xb_ld(unsigned* p)              { return __hip_atomic_load(p, __ATOMIC_RELAXED, __HIP_MEMORY_SCOPE_AGENT); }
; __device__ __forceinline__ unsigned xb_add(unsigned* p, unsigned v) { return __hip_atomic_fetch_add(p, v, __ATOMIC_RELAXED, __HIP_MEMORY_SCOPE_AGENT); }
; #define XB_SPIN(cond, bar) do { unsigned _sp = 0; while (cond) { __builtin_amdgcn_s_sleep(1); \
;     if ((++_sp & 255u) == 0u) { if (xb_ld(&(bar)[XB_TMO])) break; if (_sp > XB_SPIN_CAP) { atomicAdd(&(bar)[XB_TMO], 1u); break; } } } } while (0)
; __device__ __forceinline__ void xcd_barrier(const XcdBarrier& b) {
;     ...
;         const unsigned old = xb_add(&bar[XB_XSUB(b.x)], 1u);
;         const unsigned gen = old / nloc;
;         if (old + 1u == (gen + 1u) * nloc) {
;             __builtin_amdgcn_fence(__ATOMIC_RELEASE, "agent");
;             asm volatile("s_waitcnt vmcnt(0)" ::: "memory");
;             const unsigned og = xb_add(&bar[XB_TOP], 1u);
;             const unsigned tg = og / nx;
;             if (og + 1u == (tg + 1u) * nx) xb_add(&bar[XB_TOPGEN], 1u);
;             else XB_SPIN(xb_ld(&bar[XB_TOPGEN]) == tg, bar);
;             __builtin_amdgcn_fence(__ATOMIC_ACQUIRE, "agent");
;             xb_add(&bar[XB_XGEN(b.x)], 1u);
;             asm volatile("s_waitcnt vmcnt(0)" ::: "memory");
;         } else {
;             XB_SPIN(xb_ld(&bar[XB_XGEN(b.x)]) == gen, bar);
.LBB0_607:
	s_or_b64 exec, exec, s[8:9]
	v_cvt_f32_u32_e32 v4, v2
	s_waitcnt vmcnt(0)
	v_readfirstlane_b32 s8, v3
	v_sub_u32_e32 v3, 0, v2
	v_rcp_iflag_f32_e32 v4, v4
	v_add_u32_e32 v5, s8, v1
	v_mul_f32_e32 v4, 0x4f7ffffe, v4
	v_cvt_u32_f32_e32 v4, v4
	v_mul_lo_u32 v1, v3, v4
	v_mul_hi_u32 v1, v4, v1
	v_add_u32_e32 v1, v4, v1
	v_mul_hi_u32 v1, v5, v1
	v_mul_lo_u32 v3, v1, v2
	v_sub_u32_e32 v3, v5, v3
	v_add_u32_e32 v4, 1, v1
	v_cmp_ge_u32_e32 vcc, v3, v2
	s_nop 1
	v_cndmask_b32_e32 v1, v1, v4, vcc
	v_sub_u32_e32 v4, v3, v2
	v_cndmask_b32_e32 v3, v3, v4, vcc
	v_add_u32_e32 v4, 1, v1
	v_cmp_ge_u32_e32 vcc, v3, v2
	v_add_u32_e32 v3, 1, v5
	s_nop 0
	v_cndmask_b32_e32 v1, v1, v4, vcc
	v_mul_lo_u32 v4, v2, v1
	v_add_u32_e32 v2, v4, v2
	v_cmp_ne_u32_e32 vcc, v3, v2
	s_and_saveexec_b64 s[8:9], vcc
	s_xor_b64 s[8:9], exec, s[8:9]
	s_cbranch_execz .LBB0_621
	s_waitcnt lgkmcnt(0)
	v_mov_b32_e32 v0, 0
	v_readlane_b32 s98, v242, 30
	v_readlane_b32 s99, v242, 31
	s_nop 4
	s_add_u32 s98, s98, 0x3300
	s_addc_u32 s99, s99, 0
	global_load_dword v2, v0, s[98:99] sc1
	s_waitcnt vmcnt(0)
	v_cmp_eq_u32_e32 vcc, v2, v1
	s_and_saveexec_b64 s[10:11], vcc
	s_cbranch_execz .LBB0_620
	s_mov_b32 s16, 1
	s_mov_b64 s[12:13], 0
	s_branch .LBB0_611

; __device__ __forceinline__ unsigned xb_ld(unsigned* p)              { return __hip_atomic_load(p, __ATOMIC_RELAXED, __HIP_MEMORY_SCOPE_AGENT); }
; __device__ __forceinline__ unsigned xb_add(unsigned* p, unsigned v) { return __hip_atomic_fetch_add(p, v, __ATOMIC_RELAXED, __HIP_MEMORY_SCOPE_AGENT); }
; #define XB_SPIN(cond, bar) do { unsigned _sp = 0; while (cond) { __builtin_amdgcn_s_sleep(1); \
;     if ((++_sp & 255u) == 0u) { if (xb_ld(&(bar)[XB_TMO])) break; if (_sp > XB_SPIN_CAP) { atomicAdd(&(bar)[XB_TMO], 1u); break; } } } } while (0)
; __device__ __forceinline__ void xcd_barrier(const XcdBarrier& b) {
;     ...
;             else XB_SPIN(xb_ld(&bar[XB_TOPGEN]) == tg, bar);
;             __builtin_amdgcn_fence(__ATOMIC_ACQUIRE, "agent");
;             xb_add(&bar[XB_XGEN(b.x)], 1u);
;             asm volatile("s_waitcnt vmcnt(0)" ::: "memory");
;         } else {
;             XB_SPIN(xb_ld(&bar[XB_XGEN(b.x)]) == gen, bar);
.LBB0_613:
	global_load_dword v2, v0, s[98:99] sc1
	s_add_i32 s16, s16, 1
	s_mov_b64 s[24:25], -1
	s_waitcnt vmcnt(0)
	v_cmp_ne_u32_e32 vcc, v2, v1
	s_orn2_b64 s[20:21], vcc, exec
	s_branch .LBB0_610

; __device__ __forceinline__ unsigned xb_ld(unsigned* p)              { return __hip_atomic_load(p, __ATOMIC_RELAXED, __HIP_MEMORY_SCOPE_AGENT); }
; __device__ __forceinline__ unsigned xb_add(unsigned* p, unsigned v) { return __hip_atomic_fetch_add(p, v, __ATOMIC_RELAXED, __HIP_MEMORY_SCOPE_AGENT); }
; #define XB_SPIN(cond, bar) do { unsigned _sp = 0; while (cond) { __builtin_amdgcn_s_sleep(1); \
;     if ((++_sp & 255u) == 0u) { if (xb_ld(&(bar)[XB_TMO])) break; if (_sp > XB_SPIN_CAP) { atomicAdd(&(bar)[XB_TMO], 1u); break; } } } } while (0)
; __device__ __forceinline__ void xcd_barrier(const XcdBarrier& b) {
;     ...
;         const unsigned old = xb_add(&bar[XB_XSUB(b.x)], 1u);
;         const unsigned gen = old / nloc;
;         if (old + 1u == (gen + 1u) * nloc) {
;             __builtin_amdgcn_fence(__ATOMIC_RELEASE, "agent");
;             asm volatile("s_waitcnt vmcnt(0)" ::: "memory");
;             const unsigned og = xb_add(&bar[XB_TOP], 1u);
;             const unsigned tg = og / nx;
;             if (og + 1u == (tg + 1u) * nx) xb_add(&bar[XB_TOPGEN], 1u);
;             else XB_SPIN(xb_ld(&bar[XB_TOPGEN]) == tg, bar);
;             __builtin_amdgcn_fence(__ATOMIC_ACQUIRE, "agent");
;             xb_add(&bar[XB_XGEN(b.x)], 1u);
;             asm volatile("s_waitcnt vmcnt(0)" ::: "memory");
;         } else {
;             XB_SPIN(xb_ld(&bar[XB_XGEN(b.x)]) == gen, bar);
.LBB0_735:
	s_or_b64 exec, exec, s[6:7]
	v_cvt_f32_u32_e32 v4, v2
	s_waitcnt vmcnt(0)
	v_readfirstlane_b32 s6, v3
	v_sub_u32_e32 v3, 0, v2
	v_rcp_iflag_f32_e32 v4, v4
	v_add_u32_e32 v5, s6, v1
	v_mul_f32_e32 v4, 0x4f7ffffe, v4
	v_cvt_u32_f32_e32 v4, v4
	v_mul_lo_u32 v1, v3, v4
	v_mul_hi_u32 v1, v4, v1
	v_add_u32_e32 v1, v4, v1
	v_mul_hi_u32 v1, v5, v1
	v_mul_lo_u32 v3, v1, v2
	v_sub_u32_e32 v3, v5, v3
	v_add_u32_e32 v4, 1, v1
	v_cmp_ge_u32_e32 vcc, v3, v2
	s_nop 1
	v_cndmask_b32_e32 v1, v1, v4, vcc
	v_sub_u32_e32 v4, v3, v2
	v_cndmask_b32_e32 v3, v3, v4, vcc
	v_add_u32_e32 v4, 1, v1
	v_cmp_ge_u32_e32 vcc, v3, v2
	v_add_u32_e32 v3, 1, v5
	s_nop 0
	v_cndmask_b32_e32 v1, v1, v4, vcc
	v_mul_lo_u32 v4, v2, v1
	v_add_u32_e32 v2, v4, v2
	v_cmp_ne_u32_e32 vcc, v3, v2
	s_and_saveexec_b64 s[6:7], vcc
	s_xor_b64 s[6:7], exec, s[6:7]
	s_cbranch_execz .LBB0_749
	s_waitcnt lgkmcnt(0)
	v_mov_b32_e32 v0, 0
	s_add_u32 s98, s28, 0x3300
	s_addc_u32 s99, s29, 0
	global_load_dword v2, v0, s[98:99] sc1
	s_waitcnt vmcnt(0)
	v_cmp_eq_u32_e32 vcc, v2, v1
	s_and_saveexec_b64 s[8:9], vcc
	s_cbranch_execz .LBB0_748
	s_mov_b32 s20, 1
	s_mov_b64 s[10:11], 0
	s_branch .LBB0_739

; __device__ __forceinline__ unsigned xb_ld(unsigned* p)              { return __hip_atomic_load(p, __ATOMIC_RELAXED, __HIP_MEMORY_SCOPE_AGENT); }
; __device__ __forceinline__ unsigned xb_add(unsigned* p, unsigned v) { return __hip_atomic_fetch_add(p, v, __ATOMIC_RELAXED, __HIP_MEMORY_SCOPE_AGENT); }
; #define XB_SPIN(cond, bar) do { unsigned _sp = 0; while (cond) { __builtin_amdgcn_s_sleep(1); \
;     if ((++_sp & 255u) == 0u) { if (xb_ld(&(bar)[XB_TMO])) break; if (_sp > XB_SPIN_CAP) { atomicAdd(&(bar)[XB_TMO], 1u); break; } } } } while (0)
; __device__ __forceinline__ void xcd_barrier(const XcdBarrier& b) {
;     ...
;             else XB_SPIN(xb_ld(&bar[XB_TOPGEN]) == tg, bar);
;             __builtin_amdgcn_fence(__ATOMIC_ACQUIRE, "agent");
;             xb_add(&bar[XB_XGEN(b.x)], 1u);
;             asm volatile("s_waitcnt vmcnt(0)" ::: "memory");
;         } else {
;             XB_SPIN(xb_ld(&bar[XB_XGEN(b.x)]) == gen, bar);
.LBB0_741:
	global_load_dword v2, v0, s[98:99] sc1
	s_add_i32 s20, s20, 1
	s_mov_b64 s[16:17], -1
	s_waitcnt vmcnt(0)
	v_cmp_ne_u32_e32 vcc, v2, v1
	s_orn2_b64 s[14:15], vcc, exec
	s_branch .LBB0_738

; __device__ __forceinline__ unsigned xb_ld(unsigned* p)              { return __hip_atomic_load(p, __ATOMIC_RELAXED, __HIP_MEMORY_SCOPE_AGENT); }
; __device__ __forceinline__ unsigned xb_add(unsigned* p, unsigned v) { return __hip_atomic_fetch_add(p, v, __ATOMIC_RELAXED, __HIP_MEMORY_SCOPE_AGENT); }
; #define XB_SPIN(cond, bar) do { unsigned _sp = 0; while (cond) { __builtin_amdgcn_s_sleep(1); \
;     if ((++_sp & 255u) == 0u) { if (xb_ld(&(bar)[XB_TMO])) break; if (_sp > XB_SPIN_CAP) { atomicAdd(&(bar)[XB_TMO], 1u); break; } } } } while (0)
; __device__ __forceinline__ void xcd_barrier(const XcdBarrier& b) {
;     ...
;         const unsigned old = xb_add(&bar[XB_XSUB(b.x)], 1u);
;         const unsigned gen = old / nloc;
;         if (old + 1u == (gen + 1u) * nloc) {
;             __builtin_amdgcn_fence(__ATOMIC_RELEASE, "agent");
;             asm volatile("s_waitcnt vmcnt(0)" ::: "memory");
;             const unsigned og = xb_add(&bar[XB_TOP], 1u);
;             const unsigned tg = og / nx;
;             if (og + 1u == (tg + 1u) * nx) xb_add(&bar[XB_TOPGEN], 1u);
;             else XB_SPIN(xb_ld(&bar[XB_TOPGEN]) == tg, bar);
;             __builtin_amdgcn_fence(__ATOMIC_ACQUIRE, "agent");
;             xb_add(&bar[XB_XGEN(b.x)], 1u);
;             asm volatile("s_waitcnt vmcnt(0)" ::: "memory");
;         } else {
;             XB_SPIN(xb_ld(&bar[XB_XGEN(b.x)]) == gen, bar);
.LBB0_917:
	s_or_b64 exec, exec, s[8:9]
	v_cvt_f32_u32_e32 v4, v2
	s_waitcnt vmcnt(0)
	v_readfirstlane_b32 s8, v3
	v_sub_u32_e32 v3, 0, v2
	v_rcp_iflag_f32_e32 v4, v4
	v_add_u32_e32 v5, s8, v1
	v_mul_f32_e32 v4, 0x4f7ffffe, v4
	v_cvt_u32_f32_e32 v4, v4
	v_mul_lo_u32 v1, v3, v4
	v_mul_hi_u32 v1, v4, v1
	v_add_u32_e32 v1, v4, v1
	v_mul_hi_u32 v1, v5, v1
	v_mul_lo_u32 v3, v1, v2
	v_sub_u32_e32 v3, v5, v3
	v_add_u32_e32 v4, 1, v1
	v_cmp_ge_u32_e32 vcc, v3, v2
	s_nop 1
	v_cndmask_b32_e32 v1, v1, v4, vcc
	v_sub_u32_e32 v4, v3, v2
	v_cndmask_b32_e32 v3, v3, v4, vcc
	v_add_u32_e32 v4, 1, v1
	v_cmp_ge_u32_e32 vcc, v3, v2
	v_add_u32_e32 v3, 1, v5
	s_nop 0
	v_cndmask_b32_e32 v1, v1, v4, vcc
	v_mul_lo_u32 v4, v2, v1
	v_add_u32_e32 v2, v4, v2
	v_cmp_ne_u32_e32 vcc, v3, v2
	s_and_saveexec_b64 s[8:9], vcc
	s_xor_b64 s[8:9], exec, s[8:9]
	s_cbranch_execz .LBB0_931
	s_waitcnt lgkmcnt(0)
	v_mov_b32_e32 v0, 0
	s_add_u32 s98, s28, 0x3300
	s_addc_u32 s99, s29, 0
	global_load_dword v2, v0, s[98:99] sc1
	s_waitcnt vmcnt(0)
	v_cmp_eq_u32_e32 vcc, v2, v1
	s_and_saveexec_b64 s[10:11], vcc
	s_cbranch_execz .LBB0_930
	s_mov_b32 s22, 1
	s_mov_b64 s[12:13], 0
	s_branch .LBB0_921

; __device__ __forceinline__ unsigned xb_ld(unsigned* p)              { return __hip_atomic_load(p, __ATOMIC_RELAXED, __HIP_MEMORY_SCOPE_AGENT); }
; __device__ __forceinline__ unsigned xb_add(unsigned* p, unsigned v) { return __hip_atomic_fetch_add(p, v, __ATOMIC_RELAXED, __HIP_MEMORY_SCOPE_AGENT); }
; #define XB_SPIN(cond, bar) do { unsigned _sp = 0; while (cond) { __builtin_amdgcn_s_sleep(1); \
;     if ((++_sp & 255u) == 0u) { if (xb_ld(&(bar)[XB_TMO])) break; if (_sp > XB_SPIN_CAP) { atomicAdd(&(bar)[XB_TMO], 1u); break; } } } } while (0)
; __device__ __forceinline__ void xcd_barrier(const XcdBarrier& b) {
;     ...
;             else XB_SPIN(xb_ld(&bar[XB_TOPGEN]) == tg, bar);
;             __builtin_amdgcn_fence(__ATOMIC_ACQUIRE, "agent");
;             xb_add(&bar[XB_XGEN(b.x)], 1u);
;             asm volatile("s_waitcnt vmcnt(0)" ::: "memory");
;         } else {
;             XB_SPIN(xb_ld(&bar[XB_XGEN(b.x)]) == gen, bar);
.LBB0_923:
	global_load_dword v2, v0, s[98:99] sc1
	s_add_i32 s22, s22, 1
	s_mov_b64 s[18:19], -1
	s_waitcnt vmcnt(0)
	v_cmp_ne_u32_e32 vcc, v2, v1
	s_orn2_b64 s[16:17], vcc, exec
	s_branch .LBB0_920

; __device__ __forceinline__ unsigned xb_ld(unsigned* p)              { return __hip_atomic_load(p, __ATOMIC_RELAXED, __HIP_MEMORY_SCOPE_AGENT); }
; __device__ __forceinline__ unsigned xb_add(unsigned* p, unsigned v) { return __hip_atomic_fetch_add(p, v, __ATOMIC_RELAXED, __HIP_MEMORY_SCOPE_AGENT); }
; #define XB_SPIN(cond, bar) do { unsigned _sp = 0; while (cond) { __builtin_amdgcn_s_sleep(1); \
;     if ((++_sp & 255u) == 0u) { if (xb_ld(&(bar)[XB_TMO])) break; if (_sp > XB_SPIN_CAP) { atomicAdd(&(bar)[XB_TMO], 1u); break; } } } } while (0)
; __device__ __forceinline__ void xcd_barrier(const XcdBarrier& b) {
;     ...
;         const unsigned old = xb_add(&bar[XB_XSUB(b.x)], 1u);
;         const unsigned gen = old / nloc;
;         if (old + 1u == (gen + 1u) * nloc) {
;             __builtin_amdgcn_fence(__ATOMIC_RELEASE, "agent");
;             asm volatile("s_waitcnt vmcnt(0)" ::: "memory");
;             const unsigned og = xb_add(&bar[XB_TOP], 1u);
;             const unsigned tg = og / nx;
;             if (og + 1u == (tg + 1u) * nx) xb_add(&bar[XB_TOPGEN], 1u);
;             else XB_SPIN(xb_ld(&bar[XB_TOPGEN]) == tg, bar);
;             __builtin_amdgcn_fence(__ATOMIC_ACQUIRE, "agent");
;             xb_add(&bar[XB_XGEN(b.x)], 1u);
;             asm volatile("s_waitcnt vmcnt(0)" ::: "memory");
;         } else {
;             XB_SPIN(xb_ld(&bar[XB_XGEN(b.x)]) == gen, bar);
.LBB0_1018:
	s_or_b64 exec, exec, s[4:5]
	v_cvt_f32_u32_e32 v4, v2
	s_waitcnt vmcnt(0)
	v_readfirstlane_b32 s4, v3
	v_sub_u32_e32 v3, 0, v2
	v_rcp_iflag_f32_e32 v4, v4
	v_add_u32_e32 v5, s4, v1
	v_mul_f32_e32 v4, 0x4f7ffffe, v4
	v_cvt_u32_f32_e32 v4, v4
	v_mul_lo_u32 v1, v3, v4
	v_mul_hi_u32 v1, v4, v1
	v_add_u32_e32 v1, v4, v1
	v_mul_hi_u32 v1, v5, v1
	v_mul_lo_u32 v3, v1, v2
	v_sub_u32_e32 v3, v5, v3
	v_add_u32_e32 v4, 1, v1
	v_cmp_ge_u32_e32 vcc, v3, v2
	s_nop 1
	v_cndmask_b32_e32 v1, v1, v4, vcc
	v_sub_u32_e32 v4, v3, v2
	v_cndmask_b32_e32 v3, v3, v4, vcc
	v_add_u32_e32 v4, 1, v1
	v_cmp_ge_u32_e32 vcc, v3, v2
	v_add_u32_e32 v3, 1, v5
	s_nop 0
	v_cndmask_b32_e32 v1, v1, v4, vcc
	v_mul_lo_u32 v4, v2, v1
	v_add_u32_e32 v2, v4, v2
	v_cmp_ne_u32_e32 vcc, v3, v2
	s_and_saveexec_b64 s[4:5], vcc
	s_xor_b64 s[4:5], exec, s[4:5]
	s_cbranch_execz .LBB0_1032
	s_waitcnt lgkmcnt(0)
	v_mov_b32_e32 v0, 0
	s_add_u32 s98, s28, 0x3300
	s_addc_u32 s99, s29, 0
	global_load_dword v2, v0, s[98:99] sc1
	s_waitcnt vmcnt(0)
	v_cmp_eq_u32_e32 vcc, v2, v1
	s_and_saveexec_b64 s[6:7], vcc
	s_cbranch_execz .LBB0_1031
	s_mov_b32 s22, 1
	s_mov_b64 s[8:9], 0
	s_branch .LBB0_1022

; __device__ __forceinline__ unsigned xb_ld(unsigned* p)              { return __hip_atomic_load(p, __ATOMIC_RELAXED, __HIP_MEMORY_SCOPE_AGENT); }
; __device__ __forceinline__ unsigned xb_add(unsigned* p, unsigned v) { return __hip_atomic_fetch_add(p, v, __ATOMIC_RELAXED, __HIP_MEMORY_SCOPE_AGENT); }
; #define XB_SPIN(cond, bar) do { unsigned _sp = 0; while (cond) { __builtin_amdgcn_s_sleep(1); \
;     if ((++_sp & 255u) == 0u) { if (xb_ld(&(bar)[XB_TMO])) break; if (_sp > XB_SPIN_CAP) { atomicAdd(&(bar)[XB_TMO], 1u); break; } } } } while (0)
; __device__ __forceinline__ void xcd_barrier(const XcdBarrier& b) {
;     ...
;             else XB_SPIN(xb_ld(&bar[XB_TOPGEN]) == tg, bar);
;             __builtin_amdgcn_fence(__ATOMIC_ACQUIRE, "agent");
;             xb_add(&bar[XB_XGEN(b.x)], 1u);
;             asm volatile("s_waitcnt vmcnt(0)" ::: "memory");
;         } else {
;             XB_SPIN(xb_ld(&bar[XB_XGEN(b.x)]) == gen, bar);
.LBB0_1024:
	global_load_dword v2, v0, s[98:99] sc1
	s_add_i32 s22, s22, 1
	s_mov_b64 s[18:19], -1
	s_waitcnt vmcnt(0)
	v_cmp_ne_u32_e32 vcc, v2, v1
	s_orn2_b64 s[12:13], vcc, exec
	s_branch .LBB0_1021

; __device__ __forceinline__ unsigned xb_ld(unsigned* p)              { return __hip_atomic_load(p, __ATOMIC_RELAXED, __HIP_MEMORY_SCOPE_AGENT); }
; __device__ __forceinline__ unsigned xb_add(unsigned* p, unsigned v) { return __hip_atomic_fetch_add(p, v, __ATOMIC_RELAXED, __HIP_MEMORY_SCOPE_AGENT); }
; #define XB_SPIN(cond, bar) do { unsigned _sp = 0; while (cond) { __builtin_amdgcn_s_sleep(1); \
;     if ((++_sp & 255u) == 0u) { if (xb_ld(&(bar)[XB_TMO])) break; if (_sp > XB_SPIN_CAP) { atomicAdd(&(bar)[XB_TMO], 1u); break; } } } } while (0)
; __device__ __forceinline__ void xcd_barrier(const XcdBarrier& b) {
;     ...
;         const unsigned old = xb_add(&bar[XB_XSUB(b.x)], 1u);
;         const unsigned gen = old / nloc;
;         if (old + 1u == (gen + 1u) * nloc) {
;             __builtin_amdgcn_fence(__ATOMIC_RELEASE, "agent");
;             asm volatile("s_waitcnt vmcnt(0)" ::: "memory");
;             const unsigned og = xb_add(&bar[XB_TOP], 1u);
;             const unsigned tg = og / nx;
;             if (og + 1u == (tg + 1u) * nx) xb_add(&bar[XB_TOPGEN], 1u);
;             else XB_SPIN(xb_ld(&bar[XB_TOPGEN]) == tg, bar);
;             __builtin_amdgcn_fence(__ATOMIC_ACQUIRE, "agent");
;             xb_add(&bar[XB_XGEN(b.x)], 1u);
;             asm volatile("s_waitcnt vmcnt(0)" ::: "memory");
;         } else {
;             XB_SPIN(xb_ld(&bar[XB_XGEN(b.x)]) == gen, bar);
.LBB0_1218:
	s_or_b64 exec, exec, s[6:7]
	v_cvt_f32_u32_e32 v4, v2
	s_waitcnt vmcnt(0)
	v_readfirstlane_b32 s6, v3
	v_sub_u32_e32 v3, 0, v2
	v_rcp_iflag_f32_e32 v4, v4
	v_add_u32_e32 v5, s6, v1
	v_mul_f32_e32 v4, 0x4f7ffffe, v4
	v_cvt_u32_f32_e32 v4, v4
	v_mul_lo_u32 v1, v3, v4
	v_mul_hi_u32 v1, v4, v1
	v_add_u32_e32 v1, v4, v1
	v_mul_hi_u32 v1, v5, v1
	v_mul_lo_u32 v3, v1, v2
	v_sub_u32_e32 v3, v5, v3
	v_add_u32_e32 v4, 1, v1
	v_cmp_ge_u32_e32 vcc, v3, v2
	s_nop 1
	v_cndmask_b32_e32 v1, v1, v4, vcc
	v_sub_u32_e32 v4, v3, v2
	v_cndmask_b32_e32 v3, v3, v4, vcc
	v_add_u32_e32 v4, 1, v1
	v_cmp_ge_u32_e32 vcc, v3, v2
	v_add_u32_e32 v3, 1, v5
	s_nop 0
	v_cndmask_b32_e32 v1, v1, v4, vcc
	v_mul_lo_u32 v4, v2, v1
	v_add_u32_e32 v2, v4, v2
	v_cmp_ne_u32_e32 vcc, v3, v2
	s_and_saveexec_b64 s[6:7], vcc
	s_xor_b64 s[6:7], exec, s[6:7]
	s_cbranch_execz .LBB0_1232
	s_waitcnt lgkmcnt(0)
	v_mov_b32_e32 v0, 0
	s_add_u32 s98, s28, 0x3300
	s_addc_u32 s99, s29, 0
	global_load_dword v2, v0, s[98:99] sc1
	s_waitcnt vmcnt(0)
	v_cmp_eq_u32_e32 vcc, v2, v1
	s_and_saveexec_b64 s[8:9], vcc
	s_cbranch_execz .LBB0_1231
	s_mov_b32 s22, 1
	s_mov_b64 s[10:11], 0
	s_branch .LBB0_1222

; __device__ __forceinline__ unsigned xb_ld(unsigned* p)              { return __hip_atomic_load(p, __ATOMIC_RELAXED, __HIP_MEMORY_SCOPE_AGENT); }
; __device__ __forceinline__ unsigned xb_add(unsigned* p, unsigned v) { return __hip_atomic_fetch_add(p, v, __ATOMIC_RELAXED, __HIP_MEMORY_SCOPE_AGENT); }
; #define XB_SPIN(cond, bar) do { unsigned _sp = 0; while (cond) { __builtin_amdgcn_s_sleep(1); \
;     if ((++_sp & 255u) == 0u) { if (xb_ld(&(bar)[XB_TMO])) break; if (_sp > XB_SPIN_CAP) { atomicAdd(&(bar)[XB_TMO], 1u); break; } } } } while (0)
; __device__ __forceinline__ void xcd_barrier(const XcdBarrier& b) {
;     ...
;         const unsigned old = xb_add(&bar[XB_XSUB(b.x)], 1u);
;         const unsigned gen = old / nloc;
;         if (old + 1u == (gen + 1u) * nloc) {
;             __builtin_amdgcn_fence(__ATOMIC_RELEASE, "agent");
;             asm volatile("s_waitcnt vmcnt(0)" ::: "memory");
;             const unsigned og = xb_add(&bar[XB_TOP], 1u);
;             const unsigned tg = og / nx;
;             if (og + 1u == (tg + 1u) * nx) xb_add(&bar[XB_TOPGEN], 1u);
;             else XB_SPIN(xb_ld(&bar[XB_TOPGEN]) == tg, bar);
;             __builtin_amdgcn_fence(__ATOMIC_ACQUIRE, "agent");
;             xb_add(&bar[XB_XGEN(b.x)], 1u);
;             asm volatile("s_waitcnt vmcnt(0)" ::: "memory");
;         } else {
;             XB_SPIN(xb_ld(&bar[XB_XGEN(b.x)]) == gen, bar);
.LBB0_1357:
	s_or_b64 exec, exec, s[2:3]
	v_cvt_f32_u32_e32 v4, v2
	s_waitcnt vmcnt(0)
	v_readfirstlane_b32 s2, v3
	v_sub_u32_e32 v3, 0, v2
	v_rcp_iflag_f32_e32 v4, v4
	v_add_u32_e32 v5, s2, v1
	v_mul_f32_e32 v4, 0x4f7ffffe, v4
	v_cvt_u32_f32_e32 v4, v4
	v_mul_lo_u32 v1, v3, v4
	v_mul_hi_u32 v1, v4, v1
	v_add_u32_e32 v1, v4, v1
	v_mul_hi_u32 v1, v5, v1
	v_mul_lo_u32 v3, v1, v2
	v_sub_u32_e32 v3, v5, v3
	v_add_u32_e32 v4, 1, v1
	v_cmp_ge_u32_e32 vcc, v3, v2
	s_nop 1
	v_cndmask_b32_e32 v1, v1, v4, vcc
	v_sub_u32_e32 v4, v3, v2
	v_cndmask_b32_e32 v3, v3, v4, vcc
	v_add_u32_e32 v4, 1, v1
	v_cmp_ge_u32_e32 vcc, v3, v2
	v_add_u32_e32 v3, 1, v5
	s_nop 0
	v_cndmask_b32_e32 v1, v1, v4, vcc
	v_mul_lo_u32 v4, v2, v1
	v_add_u32_e32 v2, v4, v2
	v_cmp_ne_u32_e32 vcc, v3, v2
	s_and_saveexec_b64 s[2:3], vcc
	s_xor_b64 s[2:3], exec, s[2:3]
	s_cbranch_execz .LBB0_1371
	s_waitcnt lgkmcnt(0)
	v_mov_b32_e32 v0, 0
	s_add_u32 s98, s28, 0x3300
	s_addc_u32 s99, s29, 0
	global_load_dword v2, v0, s[98:99] sc1
	s_waitcnt vmcnt(0)
	v_cmp_eq_u32_e32 vcc, v2, v1
	s_and_saveexec_b64 s[4:5], vcc
	s_cbranch_execz .LBB0_1370
	s_mov_b32 s16, 1
	s_mov_b64 s[6:7], 0
	s_branch .LBB0_1361

; __device__ __forceinline__ unsigned xb_ld(unsigned* p)              { return __hip_atomic_load(p, __ATOMIC_RELAXED, __HIP_MEMORY_SCOPE_AGENT); }
; __device__ __forceinline__ unsigned xb_add(unsigned* p, unsigned v) { return __hip_atomic_fetch_add(p, v, __ATOMIC_RELAXED, __HIP_MEMORY_SCOPE_AGENT); }
; #define XB_SPIN(cond, bar) do { unsigned _sp = 0; while (cond) { __builtin_amdgcn_s_sleep(1); \
;     if ((++_sp & 255u) == 0u) { if (xb_ld(&(bar)[XB_TMO])) break; if (_sp > XB_SPIN_CAP) { atomicAdd(&(bar)[XB_TMO], 1u); break; } } } } while (0)
; __device__ __forceinline__ void xcd_barrier(const XcdBarrier& b) {
;     ...
;             else XB_SPIN(xb_ld(&bar[XB_TOPGEN]) == tg, bar);
;             __builtin_amdgcn_fence(__ATOMIC_ACQUIRE, "agent");
;             xb_add(&bar[XB_XGEN(b.x)], 1u);
;             asm volatile("s_waitcnt vmcnt(0)" ::: "memory");
;         } else {
;             XB_SPIN(xb_ld(&bar[XB_XGEN(b.x)]) == gen, bar);
.LBB0_1363:
	global_load_dword v2, v0, s[98:99] sc1
	s_add_i32 s16, s16, 1
	s_mov_b64 s[12:13], -1
	s_waitcnt vmcnt(0)
	v_cmp_ne_u32_e32 vcc, v2, v1
	s_orn2_b64 s[10:11], vcc, exec
	s_branch .LBB0_1360

; __global__ void __launch_bounds__(NTHR, 2) fwd_megakernel(Params p) {
	.amdhsa_kernel _Z14fwd_megakernel6Params
		.amdhsa_group_segment_fixed_size 0
		.amdhsa_private_segment_fixed_size 0
		.amdhsa_kernarg_size 488
		.amdhsa_user_sgpr_count 2
		.amdhsa_user_sgpr_dispatch_ptr 0
		.amdhsa_user_sgpr_queue_ptr 0
		.amdhsa_user_sgpr_kernarg_segment_ptr 1
		.amdhsa_user_sgpr_dispatch_id 0
		.amdhsa_user_sgpr_kernarg_preload_length 0
		.amdhsa_user_sgpr_kernarg_preload_offset 0
		.amdhsa_user_sgpr_private_segment_size 0
		.amdhsa_uses_dynamic_stack 0
		.amdhsa_enable_private_segment 0
		.amdhsa_system_sgpr_workgroup_id_x 1
		.amdhsa_system_sgpr_workgroup_id_y 0
		.amdhsa_system_sgpr_workgroup_id_z 0
		.amdhsa_system_sgpr_workgroup_info 0
		.amdhsa_system_vgpr_workitem_id 2
		.amdhsa_next_free_vgpr 256
		.amdhsa_next_free_sgpr 100
		.amdhsa_accum_offset 256
		.amdhsa_reserve_vcc 1
		.amdhsa_float_round_mode_32 0
		.amdhsa_float_round_mode_16_64 0
		.amdhsa_float_denorm_mode_32 3
		.amdhsa_float_denorm_mode_16_64 3
		.amdhsa_dx10_clamp 1
		.amdhsa_ieee_mode 1
		.amdhsa_fp16_overflow 0
		.amdhsa_tg_split 0
		.amdhsa_exception_fp_ieee_invalid_op 0
		.amdhsa_exception_fp_denorm_src 0
		.amdhsa_exception_fp_ieee_div_zero 0
		.amdhsa_exception_fp_ieee_overflow 0
		.amdhsa_exception_fp_ieee_underflow 0
		.amdhsa_exception_fp_ieee_inexact 0
		.amdhsa_exception_int_div_zero 0
	.end_amdhsa_kernel

; __global__ void __launch_bounds__(NTHR, 2) fwd_megakernel(Params p) {
amdhsa.kernels:
  - .agpr_count:     0
    .args:
      - .offset:         0
        .size:           232
        .value_kind:     by_value
      - .offset:         232
        .size:           4
        .value_kind:     hidden_block_count_x
      - .offset:         236
        .size:           4
        .value_kind:     hidden_block_count_y
      - .offset:         240
        .size:           4
        .value_kind:     hidden_block_count_z
      - .offset:         244
        .size:           2
        .value_kind:     hidden_group_size_x
      - .offset:         246
        .size:           2
        .value_kind:     hidden_group_size_y
      - .offset:         248
        .size:           2
        .value_kind:     hidden_group_size_z
      - .offset:         250
        .size:           2
        .value_kind:     hidden_remainder_x
      - .offset:         252
        .size:           2
        .value_kind:     hidden_remainder_y
      - .offset:         254
        .size:           2
        .value_kind:     hidden_remainder_z
      - .offset:         272
        .size:           8
        .value_kind:     hidden_global_offset_x
      - .offset:         280
        .size:           8
        .value_kind:     hidden_global_offset_y
      - .offset:         288
        .size:           8
        .value_kind:     hidden_global_offset_z
      - .offset:         296
        .size:           2
        .value_kind:     hidden_grid_dims
      - .offset:         320
        .size:           8
        .value_kind:     hidden_multigrid_sync_arg
      - .offset:         352
        .size:           4
        .value_kind:     hidden_dynamic_lds_size
    .group_segment_fixed_size: 0
    .kernarg_segment_align: 8
    .kernarg_segment_size: 488
    .language:       OpenCL C
    .language_version:
      - 2
      - 0
    .max_flat_workgroup_size: 512
    .name:           _Z14fwd_megakernel6Params
    .private_segment_fixed_size: 0
    .sgpr_count:     106
    .sgpr_spill_count: 174
    .symbol:         _Z14fwd_megakernel6Params.kd
    .uniform_work_group_size: 1
    .uses_dynamic_stack: false
    .vgpr_count:     256
    .vgpr_spill_count: 0
    .wavefront_size: 64
